# stagger mixing-interval partner: single-tile pooling-map WGs (blockIdx>=280) s_sleep 25 before their tile so the Fourier-map tile's epilogue runs less contended
# baseline (speedup 1.0000x reference)
.LBB0_564:
	v_readlane_b32 s0, v205, 18
	s_cmp_gt_i32 s0, s2
	s_cselect_b32 s0, s2, 0
	v_mov_b32_e32 v41, v138
	s_cmp_lt_i32 s96, s0
	s_cbranch_scc1 .LBB0_574
	v_readlane_b32 s1, v206, 57
	s_or_b32 s12, s2, 0x200
	s_sub_i32 s13, s1, s0
	s_cmp_ge_i32 s13, s12
	s_cbranch_scc1 .LBB0_574
	v_readlane_b32 s1, v205, 18
	s_sub_i32 s16, s1, s0
	s_lshl_b32 s0, s50, 17
	v_readlane_b32 s1, v207, 47
	s_add_u32 s17, s1, s0
	v_readlane_b32 s0, v207, 48
	v_lshlrev_b32_e32 v0, 3, v41
	v_readlane_b32 s76, v207, 20
	s_addc_u32 s36, s0, 0
	v_and_b32_e32 v40, 0x78, v0
	v_ashrrev_i32_e32 v43, 4, v41
	s_lshl_b64 s[0:1], s[8:9], 2
	v_readlane_b32 s88, v207, 32
	v_lshlrev_b32_e32 v42, 2, v40
	v_mul_lo_u32 v0, v43, s75
	v_readlane_b32 s89, v207, 33
	s_add_u32 s0, s88, s0
	s_addc_u32 s1, s89, s1
	v_add_u32_e32 v60, v42, v0
	v_readlane_b32 s77, v207, 21
	v_readlane_b32 s78, v207, 22
	v_readlane_b32 s79, v207, 23
	v_readlane_b32 s80, v207, 24
	v_readlane_b32 s81, v207, 25
	v_readlane_b32 s82, v207, 26
	v_readlane_b32 s83, v207, 27
	v_readlane_b32 s84, v207, 28
	v_readlane_b32 s85, v207, 29
	v_readlane_b32 s86, v207, 30
	v_readlane_b32 s87, v207, 31
	v_readlane_b32 s90, v207, 34
	v_readlane_b32 s91, v207, 35
	s_cmpk_ge_u32 s96, 0x118
	s_cbranch_scc0 .Lmxp_nosleep
	s_sleep 25
.Lmxp_nosleep:
	s_branch .LBB0_568
.LBB0_567:
	s_add_i32 s13, s13, s16
	s_cmp_lt_i32 s13, s12
	s_cbranch_scc0 .LBB0_573
